# v41 + hot-loop entry alignment: .p2align 6 before the GQA and diff attention loop heads and the FFN-up GEMM main loop head
# baseline (speedup 1.0000x reference)
; #define PG8_STAGE(bufoff, gbase, voff) do { _Pragma("unroll") for (int _i = 0; _i < 2; ++_i) \
;         __builtin_amdgcn_global_load_lds((const GAS unsigned*)((const GAS char*)(gbase) + (size_t)_i * r64##voff + (vo##voff)), (LAS unsigned*)(lds + (bufoff) + ldsw + _i * 8192), 16, 0, 0); } while (0)
; #define PG8_WAIT_V(n) asm volatile("s_waitcnt vmcnt(" #n ")" ::: "memory")
; #define PG8_BAR __builtin_amdgcn_s_barrier()
; template <class Epi, class Map, bool ALIGN_EPI>
; __device__ __forceinline__ void gemm_phase(const int tid, LAS unsigned char* lds, const int lda, const int ldb, const int K, const Map& MP, const StaticOrder& S, const Epi& E) {
;     ...
;     f32x4 acc[2][2][4][2];
; #pragma unroll
;     for (int a = 0; a < 2; ++a)
; #pragma unroll
;         for (int b = 0; b < 2; ++b)
; #pragma unroll
;             for (int m = 0; m < 4; ++m)
; #pragma unroll
;                 for (int n = 0; n < 2; ++n) acc[a][b][m][n] = (f32x4){0.f, 0.f, 0.f, 0.f};
;     bf16x8 At[4][2], B0[2][2], B1[2][2];
;     const char* cA; const char* cB; MP.ptrs(cur, cA, cB);
;     PG8_STAGE(PG8_SB(0, 0), cB, B); PG8_STAGE(PG8_SB(0, 1), cB + hstepB, B); PG8_STAGE(PG8_SA(0, 0), cA, A); PG8_STAGE(PG8_SA(0, 1), cA + hstepA, A);
;     if (wr == 1) PG8_BAR;
;     PG8_WAIT_V(2); PG8_BAR;
;     PG8_STAGE(PG8_SB(1, 0), cB + kstep, B); PG8_STAGE(PG8_SA(1, 0), cA + kstep, A); PG8_STAGE(PG8_SB(1, 1), cB + hstepB + kstep, B);
;     PG8_WAIT_V(6); PG8_BAR;
;     for (;;) {
;         const bool has_next = S.next(ui + 1, nxt);
;         const char* nA = cA; const char* nB = cB; if (has_next) MP.ptrs(nxt, nA, nB);
;         for (int t = 0; t < nt; t += 2) {
.LBB0_130:
	s_add_u32 s17, s44, 0x100
	s_addc_u32 s21, s45, 0
	s_add_u32 s42, s48, 0x40080
	v_mov_b32_e32 v36, 0
	s_addc_u32 s43, s49, 0
	s_mov_b32 s48, -2
	v_mov_b32_e32 v37, v36
	v_mov_b32_e32 v38, v36
	v_mov_b32_e32 v39, v36
	v_mov_b32_e32 v128, v36
	v_mov_b32_e32 v129, v36
	v_mov_b32_e32 v130, v36
	v_mov_b32_e32 v131, v36
	v_mov_b32_e32 v32, v36
	v_mov_b32_e32 v33, v36
	v_mov_b32_e32 v34, v36
	v_mov_b32_e32 v35, v36
	v_mov_b32_e32 v44, v36
	v_mov_b32_e32 v45, v36
	v_mov_b32_e32 v46, v36
	v_mov_b32_e32 v47, v36
	v_mov_b32_e32 v132, v36
	v_mov_b32_e32 v133, v36
	v_mov_b32_e32 v134, v36
	v_mov_b32_e32 v135, v36
	v_mov_b32_e32 v40, v36
	v_mov_b32_e32 v41, v36
	v_mov_b32_e32 v42, v36
	v_mov_b32_e32 v43, v36
	v_mov_b32_e32 v4, v36
	v_mov_b32_e32 v5, v36
	v_mov_b32_e32 v6, v36
	v_mov_b32_e32 v7, v36
	v_mov_b32_e32 v64, v36
	v_mov_b32_e32 v65, v36
	v_mov_b32_e32 v66, v36
	v_mov_b32_e32 v67, v36
	v_mov_b32_e32 v0, v36
	v_mov_b32_e32 v1, v36
	v_mov_b32_e32 v2, v36
	v_mov_b32_e32 v3, v36
	v_mov_b32_e32 v16, v36
	v_mov_b32_e32 v17, v36
	v_mov_b32_e32 v18, v36
	v_mov_b32_e32 v19, v36
	v_mov_b32_e32 v68, v36
	v_mov_b32_e32 v69, v36
	v_mov_b32_e32 v70, v36
	v_mov_b32_e32 v71, v36
	v_mov_b32_e32 v8, v36
	v_mov_b32_e32 v9, v36
	v_mov_b32_e32 v10, v36
	v_mov_b32_e32 v11, v36
	v_mov_b32_e32 v20, v36
	v_mov_b32_e32 v21, v36
	v_mov_b32_e32 v22, v36
	v_mov_b32_e32 v23, v36
	v_mov_b32_e32 v72, v36
	v_mov_b32_e32 v73, v36
	v_mov_b32_e32 v74, v36
	v_mov_b32_e32 v75, v36
	v_mov_b32_e32 v12, v36
	v_mov_b32_e32 v13, v36
	v_mov_b32_e32 v14, v36
	v_mov_b32_e32 v15, v36
	v_mov_b32_e32 v28, v36
	v_mov_b32_e32 v29, v36
	v_mov_b32_e32 v30, v36
	v_mov_b32_e32 v31, v36
	v_mov_b32_e32 v76, v36
	v_mov_b32_e32 v77, v36
	v_mov_b32_e32 v78, v36
	v_mov_b32_e32 v79, v36
	v_mov_b32_e32 v24, v36
	v_mov_b32_e32 v25, v36
	v_mov_b32_e32 v26, v36
	v_mov_b32_e32 v27, v36
	v_mov_b32_e32 v84, v36
	v_mov_b32_e32 v85, v36
	v_mov_b32_e32 v86, v36
	v_mov_b32_e32 v87, v36
	v_mov_b32_e32 v88, v36
	v_mov_b32_e32 v89, v36
	v_mov_b32_e32 v90, v36
	v_mov_b32_e32 v91, v36
	v_mov_b32_e32 v92, v36
	v_mov_b32_e32 v93, v36
	v_mov_b32_e32 v94, v36
	v_mov_b32_e32 v95, v36
	v_mov_b32_e32 v100, v36
	v_mov_b32_e32 v101, v36
	v_mov_b32_e32 v102, v36
	v_mov_b32_e32 v103, v36
	v_mov_b32_e32 v140, v36
	v_mov_b32_e32 v141, v36
	v_mov_b32_e32 v142, v36
	v_mov_b32_e32 v143, v36
	v_mov_b32_e32 v144, v36
	v_mov_b32_e32 v145, v36
	v_mov_b32_e32 v146, v36
	v_mov_b32_e32 v147, v36
	v_mov_b32_e32 v48, v36
	v_mov_b32_e32 v49, v36
	v_mov_b32_e32 v50, v36
	v_mov_b32_e32 v51, v36
	v_mov_b32_e32 v136, v36
	v_mov_b32_e32 v137, v36
	v_mov_b32_e32 v138, v36
	v_mov_b32_e32 v139, v36
	v_mov_b32_e32 v56, v36
	v_mov_b32_e32 v57, v36
	v_mov_b32_e32 v58, v36
	v_mov_b32_e32 v59, v36
	v_mov_b32_e32 v152, v36
	v_mov_b32_e32 v153, v36
	v_mov_b32_e32 v154, v36
	v_mov_b32_e32 v155, v36
	v_mov_b32_e32 v52, v36
	v_mov_b32_e32 v53, v36
	v_mov_b32_e32 v54, v36
	v_mov_b32_e32 v55, v36
	v_mov_b32_e32 v148, v36
	v_mov_b32_e32 v149, v36
	v_mov_b32_e32 v150, v36
	v_mov_b32_e32 v151, v36
	v_mov_b32_e32 v60, v36
	v_mov_b32_e32 v61, v36
	v_mov_b32_e32 v62, v36
	v_mov_b32_e32 v63, v36
	v_mov_b32_e32 v156, v36
	v_mov_b32_e32 v157, v36
	v_mov_b32_e32 v158, v36
	v_mov_b32_e32 v159, v36
	.p2align	6

;     ...
;   const int lane = tid & 63, r32 = lane & 31, hi = lane >> 5; const int wid = __builtin_amdgcn_readfirstlane(tid >> 6);
;   const bf16* Qw = Qh + (long)(q0 + wid * QBLK) * KP;
;   const unsigned lds0 = (unsigned)(uintptr_t)shm;
;   float* wsf = (float*)(shm + LDS_WS) + wid * 64;
;   const bf16* ksrc = Kh + wid * 8; const unsigned kvo = (unsigned)(lane * KP) * 2u;
;   const bf16* vsrc = Vh + (long)(16 * (wid & 3)) * KP + (wid >> 2) * 32; const unsigned vvo = (unsigned)((lane >> 2) * KP + (lane & 3) * 8) * 2u;
;   const unsigned kdst = lds0 + LDS_K + wid * 1024, vdst = lds0 + LDS_V + wid * 1024;
;     ...
;   const int vb0 = (int)(lds0 + LDS_V) + ((lane >> 4) & 1) * 32 + (lane & 3) * 8 + (4 * hi + ((lane & 15) >> 2)) * 64;
;   const char* Kbase = shm + LDS_K; bf16x8 kf[8];
;   const lds_cptr shm3 = (lds_cptr)shm; const lds_cptr kp0 = shm3 + LDS_K + hi * 1024 + r32 * 16; const lds_cptr vp0 = shm3 + LDS_V + ((lane >> 4) & 1) * 32 + (lane & 3) * 8 + (4 * hi + ((lane & 15) >> 2)) * 64;
;   DMA_K(0, 0); DMA_V(0, 0); DMA_K(1, SLOTB);
;   bf16x8 qr[4];
;   #pragma unroll
;   for (int d0 = 0; d0 < 4; ++d0) qr[d0] = *reinterpret_cast<const bf16x8*>(&Qw[(long)r32 * KP + d0 * 16 + hi * 8]);
;   float z0 = 0.f; asm volatile("" : "+v"(z0)); float mhat = z0, l_reg = z0; f32x16 o[2 * DV2], negm;
;   _Pragma("unroll") for (int r = 0; r < 16; ++r) { _Pragma("unroll") for (int d_ = 0; d_ < 2 * DV2; ++d_) o[d_][r] = z0; negm[r] = z0; } asm volatile("" : "+v"(negm));
;   bool resc = false;
;     ...
;   f32x16 pA0, pA1, pB0, pB1;
;   int sl_prev = 0, sl_cur = 0, sl_next = SLOTB;
;     ...
;   DMA_K(2, 2 * SLOTB);
;   if constexpr (DV2 == 2) { WAIT_BAR(4); } else { WAIT_BAR(3); }
;   qkt(pA0, pA1, Kbase, qr, negm, r32, hi); asm volatile("s_nop 15\n\ts_nop 7" : "+v"(pA0), "+v"(pA1));
;   START(pA0, pA1);
; __global__ void __launch_bounds__(512, 2) mk_fwd(Args a) {
;     ...
;                       for (int i = 0; i < 8; ++i) {
;                           const int V = (i >> 1) * G + vcu; if (V >= 1024) break;
;                           const int c = i & 1, grp = V >> 4, qb = V & 15, b = grp >> 3, hh = grp & 7;
;                           const attn_body::bf16* base = QKV + (size_t)b * SEQ * 3072;
;                           attn_body::attn_unit<8, 3072, 2>(qb * 256, base + (2 * hh + c) * 64, base + 1024 + (2 * hh + c) * 64, base + 2048 + hh * 128,
.LBB0_475:
	s_lshr_b32 s0, s53, 1
	s_mul_i32 s0, s26, s0
	s_add_i32 s4, s72, s0
	s_cmpk_gt_i32 s4, 0x3ff
	s_mov_b64 s[0:1], -1
	s_cbranch_scc1 .LBB0_474
	v_cndmask_b32_e64 v0, 0, 1, s[46:47]
	s_lshl_b32 s1, s4, 4
	v_readfirstlane_b32 s0, v0
	s_lshl_b32 s0, s0, 7
	s_and_b32 s17, s1, 0x700
	s_or_b32 s16, s17, s0
	s_ashr_i32 s0, s4, 7
	s_and_b32 s13, s53, 1
	s_ashr_i32 s1, s0, 31
	s_mul_i32 s24, s0, 0x1800000
	s_mul_hi_i32 s19, s0, 0x1800000
	s_add_u32 s5, s2, s24
	s_addc_u32 s8, s48, s19
	s_lshl_b32 s9, s4, 8
	s_lshl_b32 s4, s4, 3
	s_and_b32 s14, s4, 0x380
	s_lshl_b32 s4, s13, 7
	s_lshl_b32 s10, s14, 1
	s_and_b32 s9, s9, 0xf00
	s_or_b32 s4, s4, s10
	s_add_u32 s20, s5, s4
	s_addc_u32 s21, s8, 0
	s_add_u32 s22, s5, s10
	v_readfirstlane_b32 s28, v239
	s_addc_u32 s23, s8, 0
	s_ashr_i32 s15, s28, 6
	s_lshl_b32 s4, s15, 5
	s_add_i32 s4, s4, s9
	s_ashr_i32 s5, s4, 31
	s_mul_i32 s9, s4, 0x1800
	s_mul_hi_i32 s8, s4, 0x1800
	s_add_u32 s30, s20, s9
	s_addc_u32 s31, s21, s8
	s_lshl_b32 s8, s15, 3
	s_ashr_i32 s9, s8, 31
	s_and_b32 s18, s28, 0x3fffffc0
	s_lshl_b64 s[10:11], s[8:9], 1
	s_add_u32 s20, s20, s10
	s_addc_u32 s21, s21, s11
	s_add_u32 s36, s20, 0x800
	s_addc_u32 s37, s21, 0
	s_lshl_b32 s8, s15, 4
	s_and_b32 s8, s8, 48
	s_mulk_i32 s8, 0x1800
	s_add_u32 s22, s22, s8
	s_addc_u32 s29, s23, 0
	s_ashr_i32 s8, s28, 3
	s_andn2_b32 s8, s8, 31
	s_ashr_i32 s9, s8, 31
	s_lshl_b64 s[8:9], s[8:9], 1
	s_add_u32 s23, s22, s8
	s_addc_u32 s34, s29, s9
	s_add_u32 s42, s23, 0x1000
	s_addc_u32 s43, s34, 0
	s_lshl_b32 s28, s15, 10
	s_cmp_lg_u32 0, -1
	s_cselect_b32 s22, 0, 0
	s_add_i32 s28, s28, s22
	s_add_i32 s29, s28, 0x6000
	s_mov_b32 s22, m0
	s_mov_b32 m0, s28
	s_nop 0
	global_load_lds_dwordx4 v241, s[36:37]
	s_mov_b32 m0, s22
	s_add_u32 s36, s23, 0x1080
	s_mov_b32 s22, m0
	s_mov_b32 m0, s29
	s_nop 0
	global_load_lds_dwordx4 v242, s[42:43]
	s_mov_b32 m0, s22
	s_addc_u32 s37, s34, 0
	s_add_i32 s22, s28, 0x8000
	s_mov_b32 s33, m0
	s_mov_b32 m0, s22
	s_nop 0
	global_load_lds_dwordx4 v242, s[36:37]
	s_mov_b32 m0, s33
	s_add_u32 s36, s20, 0x60800
	s_addc_u32 s37, s21, 0
	s_add_i32 s22, s28, 0x2000
	s_mov_b32 s33, m0
	s_mov_b32 m0, s22
	s_nop 0
	global_load_lds_dwordx4 v241, s[36:37]
	s_mov_b32 m0, s33
	v_lshl_add_u64 v[2:3], s[30:31], 0, v[216:217]
	flat_load_dwordx4 v[172:175], v[2:3]
	flat_load_dwordx4 v[168:171], v[2:3] offset:32
	flat_load_dwordx4 v[164:167], v[2:3] offset:64
	flat_load_dwordx4 v[160:163], v[2:3] offset:96
	v_mov_b32_e32 v0, v217
	s_add_u32 s30, s20, 0xc0800
	v_mov_b32_e32 v14, v0
	v_mov_b32_e32 v15, v0
	v_mov_b32_e32 v1, v0
	v_mov_b32_e32 v2, v0
	v_mov_b32_e32 v3, v0
	v_mov_b32_e32 v4, v0
	v_mov_b32_e32 v5, v0
	v_mov_b32_e32 v6, v0
	v_mov_b32_e32 v7, v0
	v_mov_b32_e32 v8, v0
	v_mov_b32_e32 v9, v0
	v_mov_b32_e32 v10, v0
	v_mov_b32_e32 v11, v0
	v_mov_b32_e32 v12, v0
	v_mov_b32_e32 v13, v0
	v_mov_b64_e32 v[30:31], v[14:15]
	v_mov_b64_e32 v[28:29], v[12:13]
	v_mov_b64_e32 v[26:27], v[10:11]
	v_mov_b64_e32 v[24:25], v[8:9]
	v_mov_b64_e32 v[22:23], v[6:7]
	v_mov_b64_e32 v[20:21], v[4:5]
	v_mov_b64_e32 v[18:19], v[2:3]
	v_mov_b64_e32 v[16:17], v[0:1]
	s_addc_u32 s31, s21, 0
	s_add_i32 s22, s28, 0x4000
	s_mov_b32 s33, m0
	s_mov_b32 m0, s22
	s_nop 0
	global_load_lds_dwordx4 v241, s[30:31]
	s_mov_b32 m0, s33
	s_waitcnt vmcnt(4) lgkmcnt(0)
	s_barrier
	ds_read_b128 v[48:51], v243
	ds_read_b128 v[52:55], v243 offset:512
	s_lshl_b32 s18, s18, 2
	s_add_i32 s18, s18, 0
	s_add_i32 s18, s18, 0x12000
	s_add_u32 s20, s20, 0x120800
	s_addc_u32 s21, s21, 0
	s_mov_b32 s30, -1
	s_mov_b32 s22, 0
	s_movk_i32 s33, 0x2000
	s_movk_i32 s31, 0x4000
	v_lshl_add_u32 v250, v240, 2, s18
	v_mov_b32_e32 v251, v0
	s_waitcnt vmcnt(0) lgkmcnt(0)
	v_mfma_f32_32x32x16_bf16 v[32:47], v[48:51], v[172:175], v[16:31]
	v_mfma_f32_32x32x16_bf16 v[16:31], v[52:55], v[172:175], v[16:31]
	ds_read_b128 v[48:51], v243 offset:2048
	ds_read_b128 v[52:55], v243 offset:2560
	s_waitcnt lgkmcnt(1)
	v_mfma_f32_32x32x16_bf16 v[32:47], v[48:51], v[168:171], v[32:47]
	s_waitcnt lgkmcnt(0)
	v_mfma_f32_32x32x16_bf16 v[16:31], v[52:55], v[168:171], v[16:31]
	ds_read_b128 v[48:51], v243 offset:4096
	ds_read_b128 v[52:55], v243 offset:4608
	s_waitcnt lgkmcnt(1)
	v_mfma_f32_32x32x16_bf16 v[32:47], v[48:51], v[164:167], v[32:47]
	s_waitcnt lgkmcnt(0)
	v_mfma_f32_32x32x16_bf16 v[16:31], v[52:55], v[164:167], v[16:31]
	ds_read_b128 v[48:51], v243 offset:6144
	ds_read_b128 v[52:55], v243 offset:6656
	s_waitcnt lgkmcnt(1)
	v_mfma_f32_32x32x16_bf16 v[32:47], v[48:51], v[160:163], v[32:47]
	s_waitcnt lgkmcnt(0)
	v_mfma_f32_32x32x16_bf16 v[16:31], v[52:55], v[160:163], v[16:31]
	s_nop 15
	s_nop 7
	s_nop 0
	v_max3_f32 v48, v32, v33, v16
	v_max3_f32 v49, v34, v35, v17
	s_nop 0
	v_max3_f32 v48, v48, v18, v19
	v_max3_f32 v49, v49, v38, v39
	s_nop 0
	v_max3_f32 v48, v48, v36, v37
	v_max3_f32 v49, v49, v22, v23
	s_nop 0
	v_max3_f32 v48, v48, v20, v21
	v_max3_f32 v49, v49, v42, v43
	s_nop 0
	v_max3_f32 v48, v48, v40, v41
	v_max3_f32 v49, v49, v26, v27
	s_nop 0
	v_max3_f32 v48, v48, v24, v25
	v_max3_f32 v49, v49, v46, v47
	s_nop 0
	v_max3_f32 v48, v48, v44, v45
	v_max3_f32 v49, v49, v30, v31
	s_nop 0
	v_max3_f32 v48, v48, v28, v29
	s_nop 0
	v_max_f32_e32 v48, v48, v49
	s_nop 0
	v_mov_b32_e32 v49, v48
	s_nop 1
	v_permlane32_swap_b32_e32 v48, v49
	v_max_f32_e32 v48, v48, v49
	s_nop 0
	v_add_f32_e32 v249, v0, v48
	v_sub_f32_e32 v32, v32, v48
	v_sub_f32_e32 v16, v16, v48
	v_sub_f32_e32 v33, v33, v48
	v_sub_f32_e32 v17, v17, v48
	v_sub_f32_e32 v34, v34, v48
	s_nop 0
	v_xor_b32_e32 v64, 0x80000000, v249
	v_mov_b32_e32 v65, v64
	v_mov_b32_e32 v66, v64
	v_mov_b32_e32 v67, v64
	v_mov_b32_e32 v68, v64
	v_mov_b32_e32 v69, v64
	v_mov_b32_e32 v70, v64
	v_mov_b32_e32 v71, v64
	v_mov_b32_e32 v72, v64
	v_mov_b32_e32 v73, v64
	v_mov_b32_e32 v74, v64
	v_mov_b32_e32 v75, v64
	v_mov_b32_e32 v76, v64
	v_mov_b32_e32 v77, v64
	v_mov_b32_e32 v78, v64
	v_mov_b32_e32 v79, v64
	s_waitcnt vmcnt(0) lgkmcnt(0)
	s_barrier
; #define WAIT_BAR(N) asm volatile("s_waitcnt vmcnt(" #N ") lgkmcnt(0)\n\ts_barrier" ::: "memory")
;   #define DMA_K(t, slot) glds16(ksrc + (long)(t) * KVBLK * KP, kvo, (unsigned)__builtin_amdgcn_readfirstlane(kdst + (slot)))
;   #define DMA_V(t, slot) do { glds16(vsrc + (long)(t) * KVBLK * KP, vvo, (unsigned)__builtin_amdgcn_readfirstlane(vdst + DV2 * (slot))); \
;     if constexpr (DV2 == 2) glds16(vsrc + 64 + (long)(t) * KVBLK * KP, vvo, (unsigned)__builtin_amdgcn_readfirstlane(vdst + DV2 * (slot) + 8192)); } while (0)
;   #define ROT() do { sl_prev = sl_cur; sl_cur = sl_next; sl_next = (sl_next == (NSLOT - 1) * SLOTB) ? 0 : sl_next + SLOTB; } while (0)
;     ...
;   f32x16 pA0, pA1, pB0, pB1;
;   int sl_prev = 0, sl_cur = 0, sl_next = SLOTB;
;     ...
;   DMA_K(2, 2 * SLOTB);
;   if constexpr (DV2 == 2) { WAIT_BAR(4); } else { WAIT_BAR(3); }
;   qkt(pA0, pA1, Kbase, qr, negm, r32, hi); asm volatile("s_nop 15\n\ts_nop 7" : "+v"(pA0), "+v"(pA1));
;   START(pA0, pA1);
;   _Pragma("unroll") for (int r = 0; r < 16; ++r) pA1[r] = __builtin_amdgcn_exp2f(pA1[r]);
;   WAIT_BAR(0);
;   DMA_K(3, 0); DMA_V(1, SLOTB);
;   ROT();
;   kload8(kf, kp0 + sl_cur);
;   if constexpr (DV2 == 2) { WAIT_BAR(3); } else { WAIT_BAR(2); }
;   s16x4 vlo[8], vhi[8]; u32x4 pw0, pw1, pw2, pw3;
	s_mov_b32 s35, m0
	s_mov_b32 m0, s28
	s_nop 0
	global_load_lds_dwordx4 v241, s[20:21]
	s_mov_b32 m0, s35
	s_add_u32 s20, s23, 0x61000
	s_addc_u32 s21, s34, 0
	s_add_i32 s35, s28, 0xa000
	s_mov_b32 s36, m0
	s_mov_b32 m0, s35
	s_nop 0
	global_load_lds_dwordx4 v242, s[20:21]
	s_mov_b32 m0, s36
	s_add_u32 s20, s23, 0x61080
	s_addc_u32 s21, s34, 0
	s_add_i32 s23, s28, 0xc000
	s_mov_b32 s34, m0
	s_mov_b32 m0, s23
	s_nop 0
	global_load_lds_dwordx4 v242, s[20:21]
	s_mov_b32 m0, s34
	s_and_b32 s20, s15, 3
	ds_read_b128 v[204:207], v243 offset:8192
	ds_read_b128 v[196:199], v243 offset:8704
	ds_read_b128 v[200:203], v243 offset:10240
	ds_read_b128 v[192:195], v243 offset:10752
	ds_read_b128 v[188:191], v243 offset:12288
	ds_read_b128 v[184:187], v243 offset:12800
	ds_read_b128 v[180:183], v243 offset:14336
	ds_read_b128 v[176:179], v243 offset:14848
	s_mul_i32 s20, s20, 0x18000
	s_or_b32 s17, s20, s17
	s_add_u32 s8, s17, s8
	s_addc_u32 s9, 0, s9
	s_add_u32 s8, s44, s8
	s_addc_u32 s9, s45, s9
	s_add_u32 s10, s10, s16
	v_sub_f32_e32 v18, v18, v48
	v_sub_f32_e32 v35, v35, v48
	v_sub_f32_e32 v19, v19, v48
	v_sub_f32_e32 v36, v36, v48
	v_sub_f32_e32 v20, v20, v48
	v_sub_f32_e32 v37, v37, v48
	v_sub_f32_e32 v21, v21, v48
	v_sub_f32_e32 v38, v38, v48
	v_sub_f32_e32 v22, v22, v48
	v_sub_f32_e32 v39, v39, v48
	v_sub_f32_e32 v23, v23, v48
	v_sub_f32_e32 v40, v40, v48
	v_sub_f32_e32 v24, v24, v48
	v_sub_f32_e32 v41, v41, v48
	v_sub_f32_e32 v25, v25, v48
	v_sub_f32_e32 v42, v42, v48
	v_sub_f32_e32 v26, v26, v48
	v_sub_f32_e32 v43, v43, v48
	v_sub_f32_e32 v27, v27, v48
	v_sub_f32_e32 v44, v44, v48
	v_sub_f32_e32 v28, v28, v48
	v_sub_f32_e32 v45, v45, v48
	v_sub_f32_e32 v29, v29, v48
	v_sub_f32_e32 v46, v46, v48
	v_sub_f32_e32 v30, v30, v48
	v_sub_f32_e32 v47, v47, v48
	v_sub_f32_e32 v31, v31, v48
	v_exp_f32_e32 v96, v32
	v_exp_f32_e32 v97, v33
	v_exp_f32_e32 v98, v34
	v_exp_f32_e32 v99, v35
	v_exp_f32_e32 v100, v36
	v_exp_f32_e32 v101, v37
	v_exp_f32_e32 v102, v38
	v_exp_f32_e32 v103, v39
	v_exp_f32_e32 v104, v40
	v_exp_f32_e32 v105, v41
	v_exp_f32_e32 v106, v42
	v_exp_f32_e32 v107, v43
	v_exp_f32_e32 v108, v44
	v_exp_f32_e32 v109, v45
	v_exp_f32_e32 v110, v46
	v_exp_f32_e32 v111, v47
	v_exp_f32_e32 v80, v16
	v_exp_f32_e32 v81, v17
	v_exp_f32_e32 v82, v18
	v_exp_f32_e32 v83, v19
	v_exp_f32_e32 v84, v20
	v_exp_f32_e32 v85, v21
	v_exp_f32_e32 v86, v22
	v_exp_f32_e32 v87, v23
	v_exp_f32_e32 v88, v24
	v_exp_f32_e32 v89, v25
	v_exp_f32_e32 v90, v26
	v_exp_f32_e32 v91, v27
	v_exp_f32_e32 v92, v28
	v_exp_f32_e32 v93, v29
	v_exp_f32_e32 v94, v30
	v_exp_f32_e32 v95, v31
	s_addc_u32 s11, s11, 0
	s_waitcnt vmcnt(3) lgkmcnt(0)
	s_barrier
	s_add_u32 s10, s44, s10
	s_addc_u32 s11, s45, s11
	v_mov_b64_e32 v[62:63], v[14:15]
	v_mov_b64_e32 v[30:31], v[14:15]
	v_mov_b64_e32 v[46:47], v[14:15]
	s_mov_b64 s[16:17], s[10:11]
	s_mov_b64 s[20:21], s[8:9]
	v_mov_b64_e32 v[60:61], v[12:13]
	v_mov_b64_e32 v[58:59], v[10:11]
	v_mov_b64_e32 v[56:57], v[8:9]
	v_mov_b64_e32 v[54:55], v[6:7]
	v_mov_b64_e32 v[52:53], v[4:5]
	v_mov_b64_e32 v[50:51], v[2:3]
	v_mov_b64_e32 v[48:49], v[0:1]
	v_mov_b64_e32 v[28:29], v[12:13]
	v_mov_b64_e32 v[26:27], v[10:11]
	v_mov_b64_e32 v[24:25], v[8:9]
	v_mov_b64_e32 v[22:23], v[6:7]
	v_mov_b64_e32 v[20:21], v[4:5]
	v_mov_b64_e32 v[18:19], v[2:3]
	v_mov_b64_e32 v[16:17], v[0:1]
	v_mov_b64_e32 v[44:45], v[12:13]
	v_mov_b64_e32 v[42:43], v[10:11]
	v_mov_b64_e32 v[40:41], v[8:9]
	v_mov_b64_e32 v[38:39], v[6:7]
	v_mov_b64_e32 v[36:37], v[4:5]
	v_mov_b64_e32 v[34:35], v[2:3]
	v_mov_b64_e32 v[32:33], v[0:1]
	.p2align	6

;     ...
;   const int lane = tid & 63, r32 = lane & 31, hi = lane >> 5; const int wid = __builtin_amdgcn_readfirstlane(tid >> 6);
;   const bf16* Qw = Qh + (long)(q0 + wid * QBLK) * KP;
;   const unsigned lds0 = (unsigned)(uintptr_t)shm;
;   float* wsf = (float*)(shm + LDS_WS) + wid * 64;
;   const bf16* ksrc = Kh + wid * 8; const unsigned kvo = (unsigned)(lane * KP) * 2u;
;   const bf16* vsrc = Vh + (long)(16 * (wid & 3)) * KP + (wid >> 2) * 32; const unsigned vvo = (unsigned)((lane >> 2) * KP + (lane & 3) * 8) * 2u;
;   const unsigned kdst = lds0 + LDS_K + wid * 1024, vdst = lds0 + LDS_V + wid * 1024;
;     ...
;   const int vb0 = (int)(lds0 + LDS_V) + ((lane >> 4) & 1) * 32 + (lane & 3) * 8 + (4 * hi + ((lane & 15) >> 2)) * 64;
;   const char* Kbase = shm + LDS_K; bf16x8 kf[8];
;   const lds_cptr shm3 = (lds_cptr)shm; const lds_cptr kp0 = shm3 + LDS_K + hi * 1024 + r32 * 16; const lds_cptr vp0 = shm3 + LDS_V + ((lane >> 4) & 1) * 32 + (lane & 3) * 8 + (4 * hi + ((lane & 15) >> 2)) * 64;
;   DMA_K(0, 0); DMA_V(0, 0); DMA_K(1, SLOTB);
;   bf16x8 qr[4];
;   #pragma unroll
;   for (int d0 = 0; d0 < 4; ++d0) qr[d0] = *reinterpret_cast<const bf16x8*>(&Qw[(long)r32 * KP + d0 * 16 + hi * 8]);
;   float z0 = 0.f; asm volatile("" : "+v"(z0)); float mhat = z0, l_reg = z0; f32x16 o[2 * DV2], negm;
;   _Pragma("unroll") for (int r = 0; r < 16; ++r) { _Pragma("unroll") for (int d_ = 0; d_ < 2 * DV2; ++d_) o[d_][r] = z0; negm[r] = z0; } asm volatile("" : "+v"(negm));
;   bool resc = false;
;     ...
;   f32x16 pA0, pA1, pB0, pB1;
;   int sl_prev = 0, sl_cur = 0, sl_next = SLOTB;
;     ...
;   DMA_K(2, 2 * SLOTB);
;   if constexpr (DV2 == 2) { WAIT_BAR(4); } else { WAIT_BAR(3); }
;   qkt(pA0, pA1, Kbase, qr, negm, r32, hi); asm volatile("s_nop 15\n\ts_nop 7" : "+v"(pA0), "+v"(pA1));
;   START(pA0, pA1);
;   _Pragma("unroll") for (int r = 0; r < 16; ++r) pA1[r] = __builtin_amdgcn_exp2f(pA1[r]);
;   WAIT_BAR(0);
;   DMA_K(3, 0); DMA_V(1, SLOTB);
;   ROT();
;   kload8(kf, kp0 + sl_cur);
;   if constexpr (DV2 == 2) { WAIT_BAR(3); } else { WAIT_BAR(2); }
;   s16x4 vlo[8], vhi[8]; u32x4 pw0, pw1, pw2, pw3;
; __global__ void __launch_bounds__(512, 2) mk_fwd(Args a) {
;     ...
;                         for (int U = vcu; U < 2048; U += G) {
;                           const int grp = U >> 6, rest = U & 63, g = rest >> 4, qb = rest & 15, b = grp >> 2, kvh = grp & 3, hq = kvh * 4 + g;
.LBB0_969:
	s_bfe_u32 s0, s2, 0x20006
	s_ashr_i32 s4, s2, 8
	s_lshl_b32 s22, s0, 7
	s_ashr_i32 s5, s4, 31
	s_mul_i32 s33, s4, 0xc00000
	s_mul_hi_i32 s30, s4, 0xc00000
	s_add_u32 s1, s48, s33
	s_addc_u32 s8, s49, s30
	s_lshl_b32 s10, s2, 2
	s_lshl_b32 s0, s0, 8
	s_and_b32 s10, s10, 0xc0
	s_lshl_b32 s9, s2, 8
	s_or_b32 s14, s0, s10
	s_and_b32 s9, s9, 0xf00
	s_lshl_b32 s0, s14, 1
	s_add_u32 s10, s1, s0
	s_addc_u32 s11, s8, 0
	s_add_u32 s15, s1, s22
	v_readfirstlane_b32 s23, v186
	s_addc_u32 s18, s8, 0
	s_ashr_i32 s13, s23, 6
	s_lshl_b32 s0, s13, 5
	s_add_i32 s0, s0, s9
	s_ashr_i32 s1, s0, 31
	s_mul_i32 s9, s0, 0xc00
	s_mul_hi_i32 s8, s0, 0xc00
	s_add_u32 s28, s10, s9
	s_addc_u32 s29, s11, s8
	s_lshl_b32 s8, s13, 3
	s_ashr_i32 s9, s8, 31
	s_lshl_b64 s[16:17], s[8:9], 1
	s_add_u32 s36, s15, s16
	s_addc_u32 s37, s18, s17
	s_add_u32 s10, s36, 0x800
	s_addc_u32 s11, s37, 0
	s_lshl_b32 s8, s13, 4
	s_and_b32 s8, s8, 48
	s_mulk_i32 s8, 0xc00
	s_add_u32 s15, s15, s8
	s_addc_u32 s18, s18, 0
	s_ashr_i32 s8, s23, 3
	s_andn2_b32 s8, s8, 31
	s_ashr_i32 s9, s8, 31
	s_lshl_b64 s[20:21], s[8:9], 1
	s_add_u32 s39, s15, s20
	s_addc_u32 s40, s18, s21
	s_add_u32 s8, s39, 0xa00
	s_addc_u32 s9, s40, 0
	s_lshl_b32 s19, s13, 10
	s_cmp_lg_u32 0, -1
	s_cselect_b32 s15, 0, 0
	s_add_i32 s18, s19, s15
	s_add_i32 s15, s18, 0x6000
	s_mov_b32 s24, m0
	s_mov_b32 m0, s18
	s_nop 0
	global_load_lds_dwordx4 v184, s[10:11]
	s_mov_b32 m0, s24
	s_add_u32 s34, s36, 0x30800
	s_mov_b32 s24, m0
	s_mov_b32 m0, s15
	s_nop 0
	global_load_lds_dwordx4 v185, s[8:9]
	s_mov_b32 m0, s24
	v_mov_b32_e32 v183, v217
	s_addc_u32 s35, s37, 0
	s_add_i32 s24, s18, 0x2000
	s_mov_b32 s31, m0
	s_mov_b32 m0, s24
	s_nop 0
	global_load_lds_dwordx4 v184, s[34:35]
	s_mov_b32 m0, s31
	v_lshl_add_u64 v[0:1], s[28:29], 0, v[182:183]
	flat_load_dwordx4 v[158:161], v[0:1]
	flat_load_dwordx4 v[154:157], v[0:1] offset:32
	flat_load_dwordx4 v[150:153], v[0:1] offset:64
	flat_load_dwordx4 v[146:149], v[0:1] offset:96
	v_mov_b32_e32 v64, v217
	s_add_u32 s28, s36, 0x60800
	v_mov_b32_e32 v65, v64
	v_mov_b32_e32 v66, v64
	v_mov_b32_e32 v67, v64
	v_mov_b32_e32 v68, v64
	v_mov_b32_e32 v69, v64
	v_mov_b32_e32 v70, v64
	v_mov_b32_e32 v71, v64
	v_mov_b32_e32 v72, v64
	v_mov_b32_e32 v73, v64
	v_mov_b32_e32 v74, v64
	v_mov_b32_e32 v75, v64
	v_mov_b32_e32 v76, v64
	v_mov_b32_e32 v77, v64
	v_mov_b32_e32 v78, v64
	v_mov_b32_e32 v79, v64
	v_mov_b64_e32 v[32:33], v[64:65]
	v_mov_b64_e32 v[34:35], v[66:67]
	v_mov_b64_e32 v[36:37], v[68:69]
	v_mov_b64_e32 v[38:39], v[70:71]
	v_mov_b64_e32 v[40:41], v[72:73]
	v_mov_b64_e32 v[42:43], v[74:75]
	v_mov_b64_e32 v[44:45], v[76:77]
	v_mov_b64_e32 v[46:47], v[78:79]
	s_addc_u32 s29, s37, 0
	s_add_i32 s24, s18, 0x4000
	s_mov_b32 s31, m0
	s_mov_b32 m0, s24
	s_nop 0
	global_load_lds_dwordx4 v184, s[28:29]
	s_mov_b32 m0, s31
	s_waitcnt vmcnt(3) lgkmcnt(0)
	s_barrier
	ds_read_b128 v[0:3], v187
	ds_read_b128 v[48:51], v187 offset:512
	s_add_u32 s34, s36, 0x90800
	s_addc_u32 s35, s37, 0
	s_add_u32 s36, s39, 0x30a00
	s_addc_u32 s37, s40, 0
	s_add_i32 s39, s18, 0x8000
	s_mov_b32 s24, -1
	s_mov_b32 s31, 0
	s_movk_i32 s29, 0x2000
	s_movk_i32 s28, 0x4000
	s_waitcnt vmcnt(0) lgkmcnt(0)
	v_mfma_f32_32x32x16_bf16 v[16:31], v[0:3], v[158:161], v[32:47]
	v_mfma_f32_32x32x16_bf16 v[0:15], v[48:51], v[158:161], v[32:47]
	ds_read_b128 v[48:51], v187 offset:2048
	ds_read_b128 v[52:55], v187 offset:2560
	s_waitcnt lgkmcnt(1)
	v_mfma_f32_32x32x16_bf16 v[16:31], v[48:51], v[154:157], v[16:31]
	s_waitcnt lgkmcnt(0)
	v_mfma_f32_32x32x16_bf16 v[0:15], v[52:55], v[154:157], v[0:15]
	ds_read_b128 v[48:51], v187 offset:4096
	ds_read_b128 v[52:55], v187 offset:4608
	s_waitcnt lgkmcnt(1)
	v_mfma_f32_32x32x16_bf16 v[16:31], v[48:51], v[150:153], v[16:31]
	ds_read_b128 v[48:51], v187 offset:6144
	s_waitcnt lgkmcnt(1)
	v_mfma_f32_32x32x16_bf16 v[0:15], v[52:55], v[150:153], v[0:15]
	ds_read_b128 v[52:55], v187 offset:6656
	s_waitcnt lgkmcnt(1)
	v_mfma_f32_32x32x16_bf16 v[16:31], v[48:51], v[146:149], v[16:31]
	s_waitcnt lgkmcnt(0)
	v_mfma_f32_32x32x16_bf16 v[0:15], v[52:55], v[146:149], v[0:15]
	s_nop 15
	s_nop 7
	s_waitcnt vmcnt(0) lgkmcnt(0)
	s_barrier
	s_mov_b32 s40, m0
	s_mov_b32 m0, s18
	s_nop 0
	global_load_lds_dwordx4 v184, s[34:35]
	s_mov_b32 m0, s40
	s_mov_b32 s34, m0
	s_mov_b32 m0, s39
	s_nop 0
	global_load_lds_dwordx4 v185, s[36:37]
	s_mov_b32 m0, s34
	ds_read_b128 v[82:85], v187 offset:8192
	ds_read_b128 v[166:169], v187 offset:8704
	ds_read_b128 v[170:173], v187 offset:10240
	ds_read_b128 v[162:165], v187 offset:10752
	ds_read_b128 v[126:129], v187 offset:12288
	ds_read_b128 v[122:125], v187 offset:12800
	ds_read_b128 v[118:121], v187 offset:14336
	ds_read_b128 v[114:117], v187 offset:14848
	s_and_b32 s34, s13, 3
	s_mul_i32 s34, s34, 0xc000
	s_or_b32 s34, s33, s34
	s_add_u32 s20, s34, s20
	s_addc_u32 s21, s30, s21
	s_add_u32 s20, s44, s20
	s_addc_u32 s21, s45, s21
	v_exp_f32_e32 v66, v16
	v_exp_f32_e32 v67, v17
	v_exp_f32_e32 v68, v18
	v_exp_f32_e32 v69, v19
	v_exp_f32_e32 v70, v20
	v_exp_f32_e32 v71, v21
	v_exp_f32_e32 v72, v22
	v_exp_f32_e32 v73, v23
	v_exp_f32_e32 v74, v24
	v_exp_f32_e32 v75, v25
	v_exp_f32_e32 v76, v26
	v_exp_f32_e32 v77, v27
	v_exp_f32_e32 v78, v28
	v_exp_f32_e32 v79, v29
	v_exp_f32_e32 v80, v30
	v_exp_f32_e32 v81, v31
	v_exp_f32_e32 v48, v0
	v_exp_f32_e32 v49, v1
	v_exp_f32_e32 v50, v2
	v_exp_f32_e32 v51, v3
	v_exp_f32_e32 v52, v4
	v_exp_f32_e32 v53, v5
	v_exp_f32_e32 v54, v6
	v_exp_f32_e32 v55, v7
	v_exp_f32_e32 v56, v8
	v_exp_f32_e32 v57, v9
	v_exp_f32_e32 v58, v10
	v_exp_f32_e32 v59, v11
	v_exp_f32_e32 v60, v12
	v_exp_f32_e32 v61, v13
	v_exp_f32_e32 v62, v14
	v_exp_f32_e32 v63, v15
	s_add_u32 s16, s33, s16
	s_waitcnt vmcnt(2) lgkmcnt(0)
	s_barrier
	s_addc_u32 s17, s30, s17
	s_add_u32 s16, s44, s16
	s_addc_u32 s17, s45, s17
	v_mov_b32_e32 v0, v64
	v_mov_b32_e32 v1, v64
	v_mov_b32_e32 v2, v64
	v_mov_b32_e32 v3, v64
	v_mov_b32_e32 v4, v64
	v_mov_b32_e32 v5, v64
	v_mov_b32_e32 v6, v64
	v_mov_b32_e32 v7, v64
	v_mov_b32_e32 v8, v64
	v_mov_b32_e32 v9, v64
	v_mov_b32_e32 v10, v64
	v_mov_b32_e32 v11, v64
	v_mov_b32_e32 v12, v64
	v_mov_b32_e32 v13, v64
	v_mov_b32_e32 v14, v64
	v_mov_b32_e32 v15, v64
	v_mov_b32_e32 v16, v64
	v_mov_b32_e32 v17, v64
	v_mov_b32_e32 v18, v64
	v_mov_b32_e32 v19, v64
	v_mov_b32_e32 v20, v64
	v_mov_b32_e32 v21, v64
	v_mov_b32_e32 v22, v64
	v_mov_b32_e32 v23, v64
	v_mov_b32_e32 v24, v64
	v_mov_b32_e32 v25, v64
	v_mov_b32_e32 v26, v64
	v_mov_b32_e32 v27, v64
	v_mov_b32_e32 v28, v64
	v_mov_b32_e32 v29, v64
	v_mov_b32_e32 v30, v64
	v_mov_b32_e32 v31, v64
	.p2align	6
